# scan chunk loop: header vmcnt ladder no longer waits for previous chunk's y stores (counts 6..2 as in the peeled chunk; loads drained once before loop entry)
# baseline (speedup 1.0000x reference)
; #define LAS __attribute__((address_space(3)))
; __device__ __forceinline__ unsigned pk2(float lo, float hi) { return f2bf(lo) | (f2bf(hi) << 16); }
; #define SSD_LDT(t0_) do { if (w == 0) rdt = DT[((size_t)b * SEQ + (t0_) + lane) * 64 + h]; } while (0)
; __device__ __forceinline__ void ssd_scan_mfma(const Ctx& c, bf16* X2, const float* DT, const float* a_log, const float* dskip, bool do_store) {
;     ...
;         for (int i = 0; i < 4; ++i) ST[i] = (f32x4){0.f, 0.f, 0.f, 0.f};
;         __syncthreads();
;         for (int i = tid; i < 17408 / 16; i += 512) *(LAS v4u*)(L + SS_SB + i * 16) = (v4u){0u, 0u, 0u, 0u};
;         v4u rB[2], rC[2], rXR; float rdt = 0.f;
;         const bf16* x2b = X2 + (size_t)b * SEQ * 6144;
;     ...
;         SSD_LOAD(0); SSD_LDT(0); SSD_CS(0); SSD_LDT(64);
;         for (int ch = 0; ch < SEQ / 64; ++ch) {
;             const int t0 = ch * 64, cb = ch & 1; LAS float* CS = (LAS float*)(L + SS_CS) + cb * 64; LAS float* DTS = (LAS float*)(L + SS_DTS) + cb * 64;
;             LAS unsigned char* SBr = L + SS_SB + cb * 17408; LAS unsigned char* SBw = L + SS_SB + (cb ^ 1) * 17408;
;             __syncthreads();
; #pragma unroll
;             for (int e = 0; e < 2; ++e) { const int cc = tid + 512 * e;
;                 *(LAS v4u*)(L + SS_B + (cc >> 4) * 272 + (cc & 15) * 16) = rB[e]; *(LAS v4u*)(L + SS_C + (cc >> 4) * 272 + (cc & 15) * 16) = rC[e]; }
;             *(LAS v4u*)(L + SS_XR + (tid >> 3) * 144 + (tid & 7) * 16) = rXR;
;             { const int sr = tid >> 3, p8 = tid & 7; const float fd = DTS[sr], fw = fd * __expf(CS[63] - CS[sr]);
;               float xv[8];
; #pragma unroll
;               for (int j = 0; j < 4; ++j) { xv[2 * j] = bflo(rXR[j]); xv[2 * j + 1] = bfhi(rXR[j]); }
;               v4u o1, o2; o1.x = pk2(xv[0] * fd, xv[1] * fd); o1.y = pk2(xv[2] * fd, xv[3] * fd); o1.z = pk2(xv[4] * fd, xv[5] * fd); o1.w = pk2(xv[6] * fd, xv[7] * fd);
;               o2.x = pk2(xv[0] * fw, xv[1] * fw); o2.y = pk2(xv[2] * fw, xv[3] * fw); o2.z = pk2(xv[4] * fw, xv[5] * fw); o2.w = pk2(xv[6] * fw, xv[7] * fw);
;               *(LAS v4u*)(L + SS_XD + sr * 144 + p8 * 16) = o1; *(LAS v4u*)(L + SS_XW + sr * 144 + p8 * 16) = o2; }
;             if (ch + 1 < SEQ / 64) { SSD_LOAD(t0 + 64); SSD_CS(cb ^ 1); if (ch + 2 < SEQ / 64) SSD_LDT(t0 + 128); }
.LBB0_467:
	s_lshl_b32 s2, s54, 6
	s_and_b32 s54, s85, 63
	s_lshl_b32 s57, s54, 2
	s_and_b32 s63, s85, 56
	s_lshl_b64 s[52:53], s[52:53], 20
	s_lshl_b32 s54, s54, 7
	s_lshl_b32 s63, s63, 5
	s_or_b32 s52, s52, s57
	v_lshl_add_u64 v[96:97], s[52:53], 0, v[82:83]
	s_add_u32 s52, s54, s56
	s_addc_u32 s53, 0, s55
	v_lshl_add_u64 v[98:99], s[52:53], 0, v[84:85]
	v_lshl_add_u64 v[100:101], s[52:53], 0, v[86:87]
	s_add_u32 s52, s63, s56
	s_addc_u32 s53, 0, s55
	v_mov_b32_e32 v18, 0
	s_waitcnt vmcnt(5)
	v_mov_b32_e32 v95, v94
	v_lshl_add_u64 v[102:103], s[52:53], 0, v[88:89]
	v_lshl_add_u64 v[104:105], s[52:53], 0, v[90:91]
	s_mov_b32 s63, 0
	v_mov_b32_e32 v19, v18
	v_mov_b32_e32 v20, v18
	v_mov_b32_e32 v21, v18
	v_mov_b32_e32 v14, v18
	v_mov_b32_e32 v15, v18
	v_mov_b32_e32 v16, v18
	v_mov_b32_e32 v17, v18
	v_mov_b32_e32 v10, v18
	v_mov_b32_e32 v11, v18
	v_mov_b32_e32 v12, v18
	v_mov_b32_e32 v13, v18
	v_mov_b32_e32 v6, v18
	v_mov_b32_e32 v7, v18
	v_mov_b32_e32 v8, v18
	v_mov_b32_e32 v9, v18
	s_waitcnt vmcnt(0)
	s_branch .LBB0_469
.LBB0_469:
	s_and_b32 s96, s63, 1
	s_lshl_b32 s52, s96, 8
	s_add_i32 s65, s52, 0
	s_add_i32 s65, s65, 0x17c00
	s_waitcnt lgkmcnt(0)
	s_barrier
	s_waitcnt vmcnt(6)
	ds_write_b128 v130, v[30:33]
	s_waitcnt vmcnt(5)
	ds_write_b128 v130, v[26:29] offset:17408
	s_waitcnt vmcnt(4)
	ds_write_b128 v131, v[38:41]
	s_waitcnt vmcnt(3)
	ds_write_b128 v131, v[34:37] offset:17408
	s_waitcnt vmcnt(2)
	ds_write_b128 v132, v[22:25] offset:34816
	v_add_u32_e32 v26, s52, v112
	v_mov_b32_e32 v27, s65
	v_lshl_add_u32 v28, v108, 2, s65
	ds_read_b32 v26, v26
	ds_read_b32 v27, v27 offset:252
	ds_read_b32 v28, v28
	v_lshlrev_b32_e32 v31, 16, v23
	v_lshlrev_b32_e32 v30, 16, v22
	v_and_b32_e32 v23, 0xffff0000, v23
	v_and_b32_e32 v22, 0xffff0000, v22
	s_waitcnt lgkmcnt(0)
	v_sub_f32_e32 v27, v27, v28
	v_mul_f32_e32 v27, 0x3fb8aa3b, v27
	v_exp_f32_e32 v27, v27
	v_and_b32_e32 v41, 0xffff0000, v25
	v_and_b32_e32 v40, 0xffff0000, v24
	v_lshlrev_b32_e32 v39, 16, v25
	v_mul_f32_e32 v28, v26, v27
	v_pk_mul_f32 v[34:35], v[26:27], v[22:23] op_sel_hi:[0,1]
	v_lshlrev_b32_e32 v38, 16, v24
	v_pk_mul_f32 v[24:25], v[26:27], v[40:41] op_sel_hi:[0,1]
	v_pk_mul_f32 v[32:33], v[26:27], v[30:31] op_sel_hi:[0,1]
	v_pk_mul_f32 v[30:31], v[28:29], v[30:31] op_sel_hi:[0,1]
	v_pk_mul_f32 v[36:37], v[28:29], v[22:23] op_sel_hi:[0,1]
	v_pk_mul_f32 v[22:23], v[26:27], v[38:39] op_sel_hi:[0,1]
	v_bfe_u32 v26, v25, 16, 1
	v_bfe_u32 v27, v24, 16, 1
	v_bfe_u32 v29, v35, 16, 1
	v_bfe_u32 v42, v34, 16, 1
	v_add3_u32 v34, v34, v42, s88
	v_add3_u32 v29, v35, v29, s88
	v_add3_u32 v24, v24, v27, s88
	v_add3_u32 v25, v25, v26, s88
	v_bfe_u32 v26, v32, 16, 1
	v_bfe_u32 v27, v33, 16, 1
	v_bfe_u32 v35, v22, 16, 1
	v_bfe_u32 v42, v23, 16, 1
	v_add3_u32 v23, v23, v42, s88
	v_add3_u32 v22, v22, v35, s88
	v_add3_u32 v27, v33, v27, s88
	v_add3_u32 v26, v32, v26, s88
	v_lshrrev_b32_e32 v26, 16, v26
	v_lshrrev_b32_e32 v27, 16, v27
	v_lshrrev_b32_e32 v22, 16, v22
	v_lshrrev_b32_e32 v23, 16, v23
	v_and_or_b32 v25, v25, s87, v23
	v_and_or_b32 v24, v24, s87, v22
	v_and_or_b32 v23, v29, s87, v27
	v_and_or_b32 v22, v34, s87, v26
	v_pk_mul_f32 v[26:27], v[28:29], v[38:39] op_sel_hi:[0,1]
	v_pk_mul_f32 v[28:29], v[28:29], v[40:41] op_sel_hi:[0,1]
	s_load_dwordx2 s[4:5], s[68:69], 0x120
	v_bfe_u32 v32, v29, 16, 1
	v_bfe_u32 v33, v28, 16, 1
	v_bfe_u32 v34, v37, 16, 1
	v_bfe_u32 v35, v36, 16, 1
	v_add3_u32 v35, v36, v35, s88
	v_add3_u32 v34, v37, v34, s88
	v_add3_u32 v28, v28, v33, s88
	v_add3_u32 v29, v29, v32, s88
	v_bfe_u32 v32, v30, 16, 1
	v_bfe_u32 v33, v31, 16, 1
	v_bfe_u32 v36, v26, 16, 1
	v_bfe_u32 v37, v27, 16, 1
	v_add3_u32 v27, v27, v37, s88
	v_add3_u32 v26, v26, v36, s88
	v_add3_u32 v31, v31, v33, s88
	v_add3_u32 v30, v30, v32, s88
	v_lshrrev_b32_e32 v30, 16, v30
	v_lshrrev_b32_e32 v31, 16, v31
	v_lshrrev_b32_e32 v26, 16, v26
	v_lshrrev_b32_e32 v27, 16, v27
	v_and_or_b32 v29, v29, s87, v27
	v_and_or_b32 v28, v28, s87, v26
	v_and_or_b32 v27, v34, s87, v31
	v_and_or_b32 v26, v35, s87, v30
	ds_write_b128 v132, v[22:25] offset:44032
	ds_write_b128 v132, v[26:29] offset:53248
	s_waitcnt lgkmcnt(0)
	v_lshl_add_u64 v[22:23], s[4:5], 0, v[102:103]
	s_mov_b32 s52, 0x234c2000
	v_add_co_u32_e32 v22, vcc, s52, v22
	s_xor_b32 s76, s96, 1
	s_nop 0
	v_addc_co_u32_e32 v23, vcc, 0, v23, vcc
	global_load_dwordx4 v[30:33], v[22:23], off
	global_load_dwordx4 v[26:29], v[22:23], off offset:2048
	v_lshl_add_u64 v[22:23], s[4:5], 0, v[104:105]
	v_add_co_u32_e32 v22, vcc, 0x234c2000, v22
	s_mov_b64 s[6:7], s[68:69]
	s_nop 0
	v_addc_co_u32_e32 v23, vcc, 0, v23, vcc
	global_load_dwordx4 v[38:41], v[22:23], off
	global_load_dwordx4 v[34:37], v[22:23], off offset:2048
	v_lshl_add_u64 v[22:23], s[4:5], 0, v[100:101]
	global_load_dwordx4 v[22:25], v[22:23], off
	s_and_b64 vcc, exec, s[50:51]
	s_cbranch_vccnz .LBB0_471
	v_mul_f32_e64 v42, v93, -v138
	s_nop 1
	v_add_f32_dpp v42, v42, v42 row_shr:1 row_mask:0xf bank_mask:0xf
	s_nop 1
	v_add_f32_dpp v42, v42, v42 row_shr:2 row_mask:0xf bank_mask:0xf
	s_nop 1
	v_add_f32_dpp v42, v42, v42 row_shr:4 row_mask:0xf bank_mask:0xf
	s_nop 1
	v_add_f32_dpp v42, v42, v42 row_shr:8 row_mask:0xf bank_mask:0xf
	s_nop 1
	v_add_f32_dpp v42, v42, v42 row_bcast:15 row_mask:0xa bank_mask:0xf
	s_nop 1
	v_add_f32_dpp v42, v42, v42 row_bcast:31 row_mask:0xc bank_mask:0xf
	s_nop 1
	v_lshl_or_b32 v43, s76, 8, v109
	v_add_u32_e32 v43, 0, v43
	v_add_u32_e32 v44, 0x17c00, v43
	ds_write_b32 v44, v42
	v_add_u32_e32 v42, 0x17e00, v43
	ds_write_b32 v42, v93
